# context final-state output uses wide batched loads and stores instead of 16 serial load-wait-store steps; modulation GEMV keeps all 64 row loads in flight
# speedup vs baseline: 1.0208x; 1.0208x over previous
.LBB0_34:
	s_or_b64 exec, exec, s[0:1]
	s_ashr_i32 s0, s13, 6
	s_mul_i32 s15, s15, 24
	s_add_i32 s0, s0, s14
	s_sub_i32 s1, s10, s15
	v_lshl_add_u32 v2, s1, 8, v0
	s_ashr_i32 s1, s0, 31
	s_lshl_b64 s[2:3], s[0:1], 10
	s_ashr_i32 s1, s12, 31
	s_add_u32 s2, s2, s12
	s_addc_u32 s1, s3, s1
	s_mulk_i32 s1, 0x6000
	s_mul_hi_u32 s3, s2, 0x6000
	v_readlane_b32 s36, v247, 17
	s_add_i32 s3, s3, s1
	s_mulk_i32 s2, 0x6000
	v_readlane_b32 s38, v247, 19
	v_readlane_b32 s39, v247, 20
	s_add_u32 s2, s38, s2
	s_addc_u32 s3, s39, s3
	v_ashrrev_i32_e32 v3, 31, v2
	v_mov_b32_e32 v6, 0
	v_lshl_add_u64 v[8:9], v[2:3], 2, s[2:3]
	v_lshlrev_b32_e32 v14, 2, v2
	s_mov_b32 s1, 0
	v_mov_b32_e32 v7, v6
	v_mov_b32_e32 v4, v6
	v_mov_b32_e32 v5, v6
	v_mov_b32_e32 v3, v6
	s_waitcnt lgkmcnt(0)
	s_barrier
	v_readlane_b32 s37, v247, 18
	v_readlane_b32 s40, v247, 21
	v_readlane_b32 s41, v247, 22
	v_readlane_b32 s42, v247, 23
	v_readlane_b32 s43, v247, 24
	v_readlane_b32 s44, v247, 25
	v_readlane_b32 s45, v247, 26
	v_readlane_b32 s46, v247, 27
	v_readlane_b32 s47, v247, 28
	v_readlane_b32 s48, v247, 29
	v_readlane_b32 s49, v247, 30
	v_readlane_b32 s50, v247, 31
	v_readlane_b32 s51, v247, 32
.LBB0_35:
	global_load_dword v96, v14, s[2:3]
	s_add_u32 s2, s2, 0x6000
	s_addc_u32 s3, s3, 0
	global_load_dword v97, v14, s[2:3]
	s_add_u32 s2, s2, 0x6000
	s_addc_u32 s3, s3, 0
	global_load_dword v98, v14, s[2:3]
	s_add_u32 s2, s2, 0x6000
	s_addc_u32 s3, s3, 0
	global_load_dword v99, v14, s[2:3]
	s_add_u32 s2, s2, 0x6000
	s_addc_u32 s3, s3, 0
	global_load_dword v100, v14, s[2:3]
	s_add_u32 s2, s2, 0x6000
	s_addc_u32 s3, s3, 0
	global_load_dword v101, v14, s[2:3]
	s_add_u32 s2, s2, 0x6000
	s_addc_u32 s3, s3, 0
	global_load_dword v102, v14, s[2:3]
	s_add_u32 s2, s2, 0x6000
	s_addc_u32 s3, s3, 0
	global_load_dword v103, v14, s[2:3]
	s_add_u32 s2, s2, 0x6000
	s_addc_u32 s3, s3, 0
	global_load_dword v104, v14, s[2:3]
	s_add_u32 s2, s2, 0x6000
	s_addc_u32 s3, s3, 0
	global_load_dword v105, v14, s[2:3]
	s_add_u32 s2, s2, 0x6000
	s_addc_u32 s3, s3, 0
	global_load_dword v106, v14, s[2:3]
	s_add_u32 s2, s2, 0x6000
	s_addc_u32 s3, s3, 0
	global_load_dword v107, v14, s[2:3]
	s_add_u32 s2, s2, 0x6000
	s_addc_u32 s3, s3, 0
	global_load_dword v108, v14, s[2:3]
	s_add_u32 s2, s2, 0x6000
	s_addc_u32 s3, s3, 0
	global_load_dword v109, v14, s[2:3]
	s_add_u32 s2, s2, 0x6000
	s_addc_u32 s3, s3, 0
	global_load_dword v110, v14, s[2:3]
	s_add_u32 s2, s2, 0x6000
	s_addc_u32 s3, s3, 0
	global_load_dword v111, v14, s[2:3]
	s_add_u32 s2, s2, 0x6000
	s_addc_u32 s3, s3, 0
	global_load_dword v112, v14, s[2:3]
	s_add_u32 s2, s2, 0x6000
	s_addc_u32 s3, s3, 0
	global_load_dword v113, v14, s[2:3]
	s_add_u32 s2, s2, 0x6000
	s_addc_u32 s3, s3, 0
	global_load_dword v114, v14, s[2:3]
	s_add_u32 s2, s2, 0x6000
	s_addc_u32 s3, s3, 0
	global_load_dword v115, v14, s[2:3]
	s_add_u32 s2, s2, 0x6000
	s_addc_u32 s3, s3, 0
	global_load_dword v116, v14, s[2:3]
	s_add_u32 s2, s2, 0x6000
	s_addc_u32 s3, s3, 0
	global_load_dword v117, v14, s[2:3]
	s_add_u32 s2, s2, 0x6000
	s_addc_u32 s3, s3, 0
	global_load_dword v118, v14, s[2:3]
	s_add_u32 s2, s2, 0x6000
	s_addc_u32 s3, s3, 0
	global_load_dword v119, v14, s[2:3]
	s_add_u32 s2, s2, 0x6000
	s_addc_u32 s3, s3, 0
	global_load_dword v120, v14, s[2:3]
	s_add_u32 s2, s2, 0x6000
	s_addc_u32 s3, s3, 0
	global_load_dword v121, v14, s[2:3]
	s_add_u32 s2, s2, 0x6000
	s_addc_u32 s3, s3, 0
	global_load_dword v122, v14, s[2:3]
	s_add_u32 s2, s2, 0x6000
	s_addc_u32 s3, s3, 0
	global_load_dword v123, v14, s[2:3]
	s_add_u32 s2, s2, 0x6000
	s_addc_u32 s3, s3, 0
	global_load_dword v124, v14, s[2:3]
	s_add_u32 s2, s2, 0x6000
	s_addc_u32 s3, s3, 0
	global_load_dword v125, v14, s[2:3]
	s_add_u32 s2, s2, 0x6000
	s_addc_u32 s3, s3, 0
	global_load_dword v126, v14, s[2:3]
	s_add_u32 s2, s2, 0x6000
	s_addc_u32 s3, s3, 0
	global_load_dword v127, v14, s[2:3]
	s_add_u32 s2, s2, 0x6000
	s_addc_u32 s3, s3, 0
	global_load_dword v128, v14, s[2:3]
	s_add_u32 s2, s2, 0x6000
	s_addc_u32 s3, s3, 0
	global_load_dword v129, v14, s[2:3]
	s_add_u32 s2, s2, 0x6000
	s_addc_u32 s3, s3, 0
	global_load_dword v130, v14, s[2:3]
	s_add_u32 s2, s2, 0x6000
	s_addc_u32 s3, s3, 0
	global_load_dword v131, v14, s[2:3]
	s_add_u32 s2, s2, 0x6000
	s_addc_u32 s3, s3, 0
	global_load_dword v132, v14, s[2:3]
	s_add_u32 s2, s2, 0x6000
	s_addc_u32 s3, s3, 0
	global_load_dword v133, v14, s[2:3]
	s_add_u32 s2, s2, 0x6000
	s_addc_u32 s3, s3, 0
	global_load_dword v134, v14, s[2:3]
	s_add_u32 s2, s2, 0x6000
	s_addc_u32 s3, s3, 0
	global_load_dword v135, v14, s[2:3]
	s_add_u32 s2, s2, 0x6000
	s_addc_u32 s3, s3, 0
	global_load_dword v136, v14, s[2:3]
	s_add_u32 s2, s2, 0x6000
	s_addc_u32 s3, s3, 0
	global_load_dword v137, v14, s[2:3]
	s_add_u32 s2, s2, 0x6000
	s_addc_u32 s3, s3, 0
	global_load_dword v138, v14, s[2:3]
	s_add_u32 s2, s2, 0x6000
	s_addc_u32 s3, s3, 0
	global_load_dword v139, v14, s[2:3]
	s_add_u32 s2, s2, 0x6000
	s_addc_u32 s3, s3, 0
	global_load_dword v140, v14, s[2:3]
	s_add_u32 s2, s2, 0x6000
	s_addc_u32 s3, s3, 0
	global_load_dword v141, v14, s[2:3]
	s_add_u32 s2, s2, 0x6000
	s_addc_u32 s3, s3, 0
	global_load_dword v160, v14, s[2:3]
	s_add_u32 s2, s2, 0x6000
	s_addc_u32 s3, s3, 0
	global_load_dword v161, v14, s[2:3]
	s_add_u32 s2, s2, 0x6000
	s_addc_u32 s3, s3, 0
	global_load_dword v162, v14, s[2:3]
	s_add_u32 s2, s2, 0x6000
	s_addc_u32 s3, s3, 0
	global_load_dword v163, v14, s[2:3]
	s_add_u32 s2, s2, 0x6000
	s_addc_u32 s3, s3, 0
	global_load_dword v164, v14, s[2:3]
	s_add_u32 s2, s2, 0x6000
	s_addc_u32 s3, s3, 0
	global_load_dword v165, v14, s[2:3]
	s_add_u32 s2, s2, 0x6000
	s_addc_u32 s3, s3, 0
	global_load_dword v166, v14, s[2:3]
	s_add_u32 s2, s2, 0x6000
	s_addc_u32 s3, s3, 0
	global_load_dword v167, v14, s[2:3]
	s_add_u32 s2, s2, 0x6000
	s_addc_u32 s3, s3, 0
	global_load_dword v168, v14, s[2:3]
	s_add_u32 s2, s2, 0x6000
	s_addc_u32 s3, s3, 0
	global_load_dword v169, v14, s[2:3]
	s_add_u32 s2, s2, 0x6000
	s_addc_u32 s3, s3, 0
	global_load_dword v170, v14, s[2:3]
	s_add_u32 s2, s2, 0x6000
	s_addc_u32 s3, s3, 0
	global_load_dword v171, v14, s[2:3]
	s_add_u32 s2, s2, 0x6000
	s_addc_u32 s3, s3, 0
	global_load_dword v172, v14, s[2:3]
	s_add_u32 s2, s2, 0x6000
	s_addc_u32 s3, s3, 0
	global_load_dword v173, v14, s[2:3]
	s_add_u32 s2, s2, 0x6000
	s_addc_u32 s3, s3, 0
	global_load_dword v174, v14, s[2:3]
	s_add_u32 s2, s2, 0x6000
	s_addc_u32 s3, s3, 0
	global_load_dword v175, v14, s[2:3]
	s_add_u32 s2, s2, 0x6000
	s_addc_u32 s3, s3, 0
	global_load_dword v176, v14, s[2:3]
	s_add_u32 s2, s2, 0x6000
	s_addc_u32 s3, s3, 0
	global_load_dword v177, v14, s[2:3]
	v_mov_b32_e32 v11, 0
	ds_read_b128 v[12:15], v11
	ds_read_b128 v[16:19], v11 offset:16
	ds_read_b128 v[20:23], v11 offset:256
	ds_read_b128 v[24:27], v11 offset:272
	ds_read_b128 v[28:31], v11 offset:512
	ds_read_b128 v[32:35], v11 offset:528
	ds_read_b128 v[36:39], v11 offset:768
	ds_read_b128 v[40:43], v11 offset:784
	ds_read_b128 v[44:47], v11 offset:1024
	ds_read_b128 v[48:51], v11 offset:1040
	s_waitcnt lgkmcnt(0)
	s_waitcnt vmcnt(63)
	v_fmac_f32_e32 v6, v96, v12
	v_fmac_f32_e32 v7, v96, v20
	v_fmac_f32_e32 v4, v96, v28
	v_fmac_f32_e32 v5, v96, v36
	v_fmac_f32_e32 v3, v96, v44
	s_waitcnt vmcnt(62)
	v_fmac_f32_e32 v6, v97, v13
	v_fmac_f32_e32 v7, v97, v21
	v_fmac_f32_e32 v4, v97, v29
	v_fmac_f32_e32 v5, v97, v37
	v_fmac_f32_e32 v3, v97, v45
	s_waitcnt vmcnt(61)
	v_fmac_f32_e32 v6, v98, v14
	v_fmac_f32_e32 v7, v98, v22
	v_fmac_f32_e32 v4, v98, v30
	v_fmac_f32_e32 v5, v98, v38
	v_fmac_f32_e32 v3, v98, v46
	s_waitcnt vmcnt(60)
	v_fmac_f32_e32 v6, v99, v15
	v_fmac_f32_e32 v7, v99, v23
	v_fmac_f32_e32 v4, v99, v31
	v_fmac_f32_e32 v5, v99, v39
	v_fmac_f32_e32 v3, v99, v47
	s_waitcnt vmcnt(59)
	v_fmac_f32_e32 v6, v100, v16
	v_fmac_f32_e32 v7, v100, v24
	v_fmac_f32_e32 v4, v100, v32
	v_fmac_f32_e32 v5, v100, v40
	v_fmac_f32_e32 v3, v100, v48
	s_waitcnt vmcnt(58)
	v_fmac_f32_e32 v6, v101, v17
	v_fmac_f32_e32 v7, v101, v25
	v_fmac_f32_e32 v4, v101, v33
	v_fmac_f32_e32 v5, v101, v41
	v_fmac_f32_e32 v3, v101, v49
	s_waitcnt vmcnt(57)
	v_fmac_f32_e32 v6, v102, v18
	v_fmac_f32_e32 v7, v102, v26
	v_fmac_f32_e32 v4, v102, v34
	v_fmac_f32_e32 v5, v102, v42
	v_fmac_f32_e32 v3, v102, v50
	s_waitcnt vmcnt(56)
	v_fmac_f32_e32 v6, v103, v19
	v_fmac_f32_e32 v7, v103, v27
	v_fmac_f32_e32 v4, v103, v35
	v_fmac_f32_e32 v5, v103, v43
	v_fmac_f32_e32 v3, v103, v51
	ds_read_b128 v[12:15], v11 offset:32
	ds_read_b128 v[16:19], v11 offset:48
	ds_read_b128 v[20:23], v11 offset:288
	ds_read_b128 v[24:27], v11 offset:304
	ds_read_b128 v[28:31], v11 offset:544
	ds_read_b128 v[32:35], v11 offset:560
	ds_read_b128 v[36:39], v11 offset:800
	ds_read_b128 v[40:43], v11 offset:816
	ds_read_b128 v[44:47], v11 offset:1056
	ds_read_b128 v[48:51], v11 offset:1072
	s_waitcnt lgkmcnt(0)
	s_waitcnt vmcnt(55)
	v_fmac_f32_e32 v6, v104, v12
	v_fmac_f32_e32 v7, v104, v20
	v_fmac_f32_e32 v4, v104, v28
	v_fmac_f32_e32 v5, v104, v36
	v_fmac_f32_e32 v3, v104, v44
	s_waitcnt vmcnt(54)
	v_fmac_f32_e32 v6, v105, v13
	v_fmac_f32_e32 v7, v105, v21
	v_fmac_f32_e32 v4, v105, v29
	v_fmac_f32_e32 v5, v105, v37
	v_fmac_f32_e32 v3, v105, v45
	s_waitcnt vmcnt(53)
	v_fmac_f32_e32 v6, v106, v14
	v_fmac_f32_e32 v7, v106, v22
	v_fmac_f32_e32 v4, v106, v30
	v_fmac_f32_e32 v5, v106, v38
	v_fmac_f32_e32 v3, v106, v46
	s_waitcnt vmcnt(52)
	v_fmac_f32_e32 v6, v107, v15
	v_fmac_f32_e32 v7, v107, v23
	v_fmac_f32_e32 v4, v107, v31
	v_fmac_f32_e32 v5, v107, v39
	v_fmac_f32_e32 v3, v107, v47
	s_waitcnt vmcnt(51)
	v_fmac_f32_e32 v6, v108, v16
	v_fmac_f32_e32 v7, v108, v24
	v_fmac_f32_e32 v4, v108, v32
	v_fmac_f32_e32 v5, v108, v40
	v_fmac_f32_e32 v3, v108, v48
	s_waitcnt vmcnt(50)
	v_fmac_f32_e32 v6, v109, v17
	v_fmac_f32_e32 v7, v109, v25
	v_fmac_f32_e32 v4, v109, v33
	v_fmac_f32_e32 v5, v109, v41
	v_fmac_f32_e32 v3, v109, v49
	s_waitcnt vmcnt(49)
	v_fmac_f32_e32 v6, v110, v18
	v_fmac_f32_e32 v7, v110, v26
	v_fmac_f32_e32 v4, v110, v34
	v_fmac_f32_e32 v5, v110, v42
	v_fmac_f32_e32 v3, v110, v50
	s_waitcnt vmcnt(48)
	v_fmac_f32_e32 v6, v111, v19
	v_fmac_f32_e32 v7, v111, v27
	v_fmac_f32_e32 v4, v111, v35
	v_fmac_f32_e32 v5, v111, v43
	v_fmac_f32_e32 v3, v111, v51
	ds_read_b128 v[12:15], v11 offset:64
	ds_read_b128 v[16:19], v11 offset:80
	ds_read_b128 v[20:23], v11 offset:320
	ds_read_b128 v[24:27], v11 offset:336
	ds_read_b128 v[28:31], v11 offset:576
	ds_read_b128 v[32:35], v11 offset:592
	ds_read_b128 v[36:39], v11 offset:832
	ds_read_b128 v[40:43], v11 offset:848
	ds_read_b128 v[44:47], v11 offset:1088
	ds_read_b128 v[48:51], v11 offset:1104
	s_waitcnt lgkmcnt(0)
	s_waitcnt vmcnt(47)
	v_fmac_f32_e32 v6, v112, v12
	v_fmac_f32_e32 v7, v112, v20
	v_fmac_f32_e32 v4, v112, v28
	v_fmac_f32_e32 v5, v112, v36
	v_fmac_f32_e32 v3, v112, v44
	s_waitcnt vmcnt(46)
	v_fmac_f32_e32 v6, v113, v13
	v_fmac_f32_e32 v7, v113, v21
	v_fmac_f32_e32 v4, v113, v29
	v_fmac_f32_e32 v5, v113, v37
	v_fmac_f32_e32 v3, v113, v45
	s_waitcnt vmcnt(45)
	v_fmac_f32_e32 v6, v114, v14
	v_fmac_f32_e32 v7, v114, v22
	v_fmac_f32_e32 v4, v114, v30
	v_fmac_f32_e32 v5, v114, v38
	v_fmac_f32_e32 v3, v114, v46
	s_waitcnt vmcnt(44)
	v_fmac_f32_e32 v6, v115, v15
	v_fmac_f32_e32 v7, v115, v23
	v_fmac_f32_e32 v4, v115, v31
	v_fmac_f32_e32 v5, v115, v39
	v_fmac_f32_e32 v3, v115, v47
	s_waitcnt vmcnt(43)
	v_fmac_f32_e32 v6, v116, v16
	v_fmac_f32_e32 v7, v116, v24
	v_fmac_f32_e32 v4, v116, v32
	v_fmac_f32_e32 v5, v116, v40
	v_fmac_f32_e32 v3, v116, v48
	s_waitcnt vmcnt(42)
	v_fmac_f32_e32 v6, v117, v17
	v_fmac_f32_e32 v7, v117, v25
	v_fmac_f32_e32 v4, v117, v33
	v_fmac_f32_e32 v5, v117, v41
	v_fmac_f32_e32 v3, v117, v49
	s_waitcnt vmcnt(41)
	v_fmac_f32_e32 v6, v118, v18
	v_fmac_f32_e32 v7, v118, v26
	v_fmac_f32_e32 v4, v118, v34
	v_fmac_f32_e32 v5, v118, v42
	v_fmac_f32_e32 v3, v118, v50
	s_waitcnt vmcnt(40)
	v_fmac_f32_e32 v6, v119, v19
	v_fmac_f32_e32 v7, v119, v27
	v_fmac_f32_e32 v4, v119, v35
	v_fmac_f32_e32 v5, v119, v43
	v_fmac_f32_e32 v3, v119, v51
	ds_read_b128 v[12:15], v11 offset:96
	ds_read_b128 v[16:19], v11 offset:112
	ds_read_b128 v[20:23], v11 offset:352
	ds_read_b128 v[24:27], v11 offset:368
	ds_read_b128 v[28:31], v11 offset:608
	ds_read_b128 v[32:35], v11 offset:624
	ds_read_b128 v[36:39], v11 offset:864
	ds_read_b128 v[40:43], v11 offset:880
	ds_read_b128 v[44:47], v11 offset:1120
	ds_read_b128 v[48:51], v11 offset:1136
	s_waitcnt lgkmcnt(0)
	s_waitcnt vmcnt(39)
	v_fmac_f32_e32 v6, v120, v12
	v_fmac_f32_e32 v7, v120, v20
	v_fmac_f32_e32 v4, v120, v28
	v_fmac_f32_e32 v5, v120, v36
	v_fmac_f32_e32 v3, v120, v44
	s_waitcnt vmcnt(38)
	v_fmac_f32_e32 v6, v121, v13
	v_fmac_f32_e32 v7, v121, v21
	v_fmac_f32_e32 v4, v121, v29
	v_fmac_f32_e32 v5, v121, v37
	v_fmac_f32_e32 v3, v121, v45
	s_waitcnt vmcnt(37)
	v_fmac_f32_e32 v6, v122, v14
	v_fmac_f32_e32 v7, v122, v22
	v_fmac_f32_e32 v4, v122, v30
	v_fmac_f32_e32 v5, v122, v38
	v_fmac_f32_e32 v3, v122, v46
	s_waitcnt vmcnt(36)
	v_fmac_f32_e32 v6, v123, v15
	v_fmac_f32_e32 v7, v123, v23
	v_fmac_f32_e32 v4, v123, v31
	v_fmac_f32_e32 v5, v123, v39
	v_fmac_f32_e32 v3, v123, v47
	s_waitcnt vmcnt(35)
	v_fmac_f32_e32 v6, v124, v16
	v_fmac_f32_e32 v7, v124, v24
	v_fmac_f32_e32 v4, v124, v32
	v_fmac_f32_e32 v5, v124, v40
	v_fmac_f32_e32 v3, v124, v48
	s_waitcnt vmcnt(34)
	v_fmac_f32_e32 v6, v125, v17
	v_fmac_f32_e32 v7, v125, v25
	v_fmac_f32_e32 v4, v125, v33
	v_fmac_f32_e32 v5, v125, v41
	v_fmac_f32_e32 v3, v125, v49
	s_waitcnt vmcnt(33)
	v_fmac_f32_e32 v6, v126, v18
	v_fmac_f32_e32 v7, v126, v26
	v_fmac_f32_e32 v4, v126, v34
	v_fmac_f32_e32 v5, v126, v42
	v_fmac_f32_e32 v3, v126, v50
	s_waitcnt vmcnt(32)
	v_fmac_f32_e32 v6, v127, v19
	v_fmac_f32_e32 v7, v127, v27
	v_fmac_f32_e32 v4, v127, v35
	v_fmac_f32_e32 v5, v127, v43
	v_fmac_f32_e32 v3, v127, v51
	ds_read_b128 v[12:15], v11 offset:128
	ds_read_b128 v[16:19], v11 offset:144
	ds_read_b128 v[20:23], v11 offset:384
	ds_read_b128 v[24:27], v11 offset:400
	ds_read_b128 v[28:31], v11 offset:640
	ds_read_b128 v[32:35], v11 offset:656
	ds_read_b128 v[36:39], v11 offset:896
	ds_read_b128 v[40:43], v11 offset:912
	ds_read_b128 v[44:47], v11 offset:1152
	ds_read_b128 v[48:51], v11 offset:1168
	s_waitcnt lgkmcnt(0)
	s_waitcnt vmcnt(31)
	v_fmac_f32_e32 v6, v128, v12
	v_fmac_f32_e32 v7, v128, v20
	v_fmac_f32_e32 v4, v128, v28
	v_fmac_f32_e32 v5, v128, v36
	v_fmac_f32_e32 v3, v128, v44
	s_waitcnt vmcnt(30)
	v_fmac_f32_e32 v6, v129, v13
	v_fmac_f32_e32 v7, v129, v21
	v_fmac_f32_e32 v4, v129, v29
	v_fmac_f32_e32 v5, v129, v37
	v_fmac_f32_e32 v3, v129, v45
	s_waitcnt vmcnt(29)
	v_fmac_f32_e32 v6, v130, v14
	v_fmac_f32_e32 v7, v130, v22
	v_fmac_f32_e32 v4, v130, v30
	v_fmac_f32_e32 v5, v130, v38
	v_fmac_f32_e32 v3, v130, v46
	s_waitcnt vmcnt(28)
	v_fmac_f32_e32 v6, v131, v15
	v_fmac_f32_e32 v7, v131, v23
	v_fmac_f32_e32 v4, v131, v31
	v_fmac_f32_e32 v5, v131, v39
	v_fmac_f32_e32 v3, v131, v47
	s_waitcnt vmcnt(27)
	v_fmac_f32_e32 v6, v132, v16
	v_fmac_f32_e32 v7, v132, v24
	v_fmac_f32_e32 v4, v132, v32
	v_fmac_f32_e32 v5, v132, v40
	v_fmac_f32_e32 v3, v132, v48
	s_waitcnt vmcnt(26)
	v_fmac_f32_e32 v6, v133, v17
	v_fmac_f32_e32 v7, v133, v25
	v_fmac_f32_e32 v4, v133, v33
	v_fmac_f32_e32 v5, v133, v41
	v_fmac_f32_e32 v3, v133, v49
	s_waitcnt vmcnt(25)
	v_fmac_f32_e32 v6, v134, v18
	v_fmac_f32_e32 v7, v134, v26
	v_fmac_f32_e32 v4, v134, v34
	v_fmac_f32_e32 v5, v134, v42
	v_fmac_f32_e32 v3, v134, v50
	s_waitcnt vmcnt(24)
	v_fmac_f32_e32 v6, v135, v19
	v_fmac_f32_e32 v7, v135, v27
	v_fmac_f32_e32 v4, v135, v35
	v_fmac_f32_e32 v5, v135, v43
	v_fmac_f32_e32 v3, v135, v51
	ds_read_b128 v[12:15], v11 offset:160
	ds_read_b128 v[16:19], v11 offset:176
	ds_read_b128 v[20:23], v11 offset:416
	ds_read_b128 v[24:27], v11 offset:432
	ds_read_b128 v[28:31], v11 offset:672
	ds_read_b128 v[32:35], v11 offset:688
	ds_read_b128 v[36:39], v11 offset:928
	ds_read_b128 v[40:43], v11 offset:944
	ds_read_b128 v[44:47], v11 offset:1184
	ds_read_b128 v[48:51], v11 offset:1200
	s_waitcnt lgkmcnt(0)
	s_waitcnt vmcnt(23)
	v_fmac_f32_e32 v6, v136, v12
	v_fmac_f32_e32 v7, v136, v20
	v_fmac_f32_e32 v4, v136, v28
	v_fmac_f32_e32 v5, v136, v36
	v_fmac_f32_e32 v3, v136, v44
	s_waitcnt vmcnt(22)
	v_fmac_f32_e32 v6, v137, v13
	v_fmac_f32_e32 v7, v137, v21
	v_fmac_f32_e32 v4, v137, v29
	v_fmac_f32_e32 v5, v137, v37
	v_fmac_f32_e32 v3, v137, v45
	s_waitcnt vmcnt(21)
	v_fmac_f32_e32 v6, v138, v14
	v_fmac_f32_e32 v7, v138, v22
	v_fmac_f32_e32 v4, v138, v30
	v_fmac_f32_e32 v5, v138, v38
	v_fmac_f32_e32 v3, v138, v46
	s_waitcnt vmcnt(20)
	v_fmac_f32_e32 v6, v139, v15
	v_fmac_f32_e32 v7, v139, v23
	v_fmac_f32_e32 v4, v139, v31
	v_fmac_f32_e32 v5, v139, v39
	v_fmac_f32_e32 v3, v139, v47
	s_waitcnt vmcnt(19)
	v_fmac_f32_e32 v6, v140, v16
	v_fmac_f32_e32 v7, v140, v24
	v_fmac_f32_e32 v4, v140, v32
	v_fmac_f32_e32 v5, v140, v40
	v_fmac_f32_e32 v3, v140, v48
	s_waitcnt vmcnt(18)
	v_fmac_f32_e32 v6, v141, v17
	v_fmac_f32_e32 v7, v141, v25
	v_fmac_f32_e32 v4, v141, v33
	v_fmac_f32_e32 v5, v141, v41
	v_fmac_f32_e32 v3, v141, v49
	s_waitcnt vmcnt(17)
	v_fmac_f32_e32 v6, v160, v18
	v_fmac_f32_e32 v7, v160, v26
	v_fmac_f32_e32 v4, v160, v34
	v_fmac_f32_e32 v5, v160, v42
	v_fmac_f32_e32 v3, v160, v50
	s_waitcnt vmcnt(16)
	v_fmac_f32_e32 v6, v161, v19
	v_fmac_f32_e32 v7, v161, v27
	v_fmac_f32_e32 v4, v161, v35
	v_fmac_f32_e32 v5, v161, v43
	v_fmac_f32_e32 v3, v161, v51
	ds_read_b128 v[12:15], v11 offset:192
	ds_read_b128 v[16:19], v11 offset:208
	ds_read_b128 v[20:23], v11 offset:448
	ds_read_b128 v[24:27], v11 offset:464
	ds_read_b128 v[28:31], v11 offset:704
	ds_read_b128 v[32:35], v11 offset:720
	ds_read_b128 v[36:39], v11 offset:960
	ds_read_b128 v[40:43], v11 offset:976
	ds_read_b128 v[44:47], v11 offset:1216
	ds_read_b128 v[48:51], v11 offset:1232
	s_waitcnt lgkmcnt(0)
	s_waitcnt vmcnt(15)
	v_fmac_f32_e32 v6, v162, v12
	v_fmac_f32_e32 v7, v162, v20
	v_fmac_f32_e32 v4, v162, v28
	v_fmac_f32_e32 v5, v162, v36
	v_fmac_f32_e32 v3, v162, v44
	s_waitcnt vmcnt(14)
	v_fmac_f32_e32 v6, v163, v13
	v_fmac_f32_e32 v7, v163, v21
	v_fmac_f32_e32 v4, v163, v29
	v_fmac_f32_e32 v5, v163, v37
	v_fmac_f32_e32 v3, v163, v45
	s_waitcnt vmcnt(13)
	v_fmac_f32_e32 v6, v164, v14
	v_fmac_f32_e32 v7, v164, v22
	v_fmac_f32_e32 v4, v164, v30
	v_fmac_f32_e32 v5, v164, v38
	v_fmac_f32_e32 v3, v164, v46
	s_waitcnt vmcnt(12)
	v_fmac_f32_e32 v6, v165, v15
	v_fmac_f32_e32 v7, v165, v23
	v_fmac_f32_e32 v4, v165, v31
	v_fmac_f32_e32 v5, v165, v39
	v_fmac_f32_e32 v3, v165, v47
	s_waitcnt vmcnt(11)
	v_fmac_f32_e32 v6, v166, v16
	v_fmac_f32_e32 v7, v166, v24
	v_fmac_f32_e32 v4, v166, v32
	v_fmac_f32_e32 v5, v166, v40
	v_fmac_f32_e32 v3, v166, v48
	s_waitcnt vmcnt(10)
	v_fmac_f32_e32 v6, v167, v17
	v_fmac_f32_e32 v7, v167, v25
	v_fmac_f32_e32 v4, v167, v33
	v_fmac_f32_e32 v5, v167, v41
	v_fmac_f32_e32 v3, v167, v49
	s_waitcnt vmcnt(9)
	v_fmac_f32_e32 v6, v168, v18
	v_fmac_f32_e32 v7, v168, v26
	v_fmac_f32_e32 v4, v168, v34
	v_fmac_f32_e32 v5, v168, v42
	v_fmac_f32_e32 v3, v168, v50
	s_waitcnt vmcnt(8)
	v_fmac_f32_e32 v6, v169, v19
	v_fmac_f32_e32 v7, v169, v27
	v_fmac_f32_e32 v4, v169, v35
	v_fmac_f32_e32 v5, v169, v43
	v_fmac_f32_e32 v3, v169, v51
	ds_read_b128 v[12:15], v11 offset:224
	ds_read_b128 v[16:19], v11 offset:240
	ds_read_b128 v[20:23], v11 offset:480
	ds_read_b128 v[24:27], v11 offset:496
	ds_read_b128 v[28:31], v11 offset:736
	ds_read_b128 v[32:35], v11 offset:752
	ds_read_b128 v[36:39], v11 offset:992
	ds_read_b128 v[40:43], v11 offset:1008
	ds_read_b128 v[44:47], v11 offset:1248
	ds_read_b128 v[48:51], v11 offset:1264
	s_waitcnt lgkmcnt(0)
	s_waitcnt vmcnt(7)
	v_fmac_f32_e32 v6, v170, v12
	v_fmac_f32_e32 v7, v170, v20
	v_fmac_f32_e32 v4, v170, v28
	v_fmac_f32_e32 v5, v170, v36
	v_fmac_f32_e32 v3, v170, v44
	s_waitcnt vmcnt(6)
	v_fmac_f32_e32 v6, v171, v13
	v_fmac_f32_e32 v7, v171, v21
	v_fmac_f32_e32 v4, v171, v29
	v_fmac_f32_e32 v5, v171, v37
	v_fmac_f32_e32 v3, v171, v45
	s_waitcnt vmcnt(5)
	v_fmac_f32_e32 v6, v172, v14
	v_fmac_f32_e32 v7, v172, v22
	v_fmac_f32_e32 v4, v172, v30
	v_fmac_f32_e32 v5, v172, v38
	v_fmac_f32_e32 v3, v172, v46
	s_waitcnt vmcnt(4)
	v_fmac_f32_e32 v6, v173, v15
	v_fmac_f32_e32 v7, v173, v23
	v_fmac_f32_e32 v4, v173, v31
	v_fmac_f32_e32 v5, v173, v39
	v_fmac_f32_e32 v3, v173, v47
	s_waitcnt vmcnt(3)
	v_fmac_f32_e32 v6, v174, v16
	v_fmac_f32_e32 v7, v174, v24
	v_fmac_f32_e32 v4, v174, v32
	v_fmac_f32_e32 v5, v174, v40
	v_fmac_f32_e32 v3, v174, v48
	s_waitcnt vmcnt(2)
	v_fmac_f32_e32 v6, v175, v17
	v_fmac_f32_e32 v7, v175, v25
	v_fmac_f32_e32 v4, v175, v33
	v_fmac_f32_e32 v5, v175, v41
	v_fmac_f32_e32 v3, v175, v49
	s_waitcnt vmcnt(1)
	v_fmac_f32_e32 v6, v176, v18
	v_fmac_f32_e32 v7, v176, v26
	v_fmac_f32_e32 v4, v176, v34
	v_fmac_f32_e32 v5, v176, v42
	v_fmac_f32_e32 v3, v176, v50
	s_waitcnt vmcnt(0)
	v_fmac_f32_e32 v6, v177, v19
	v_fmac_f32_e32 v7, v177, v27
	v_fmac_f32_e32 v4, v177, v35
	v_fmac_f32_e32 v5, v177, v43
	v_fmac_f32_e32 v3, v177, v51
	s_cmp_eq_u32 s11, 0
	v_mov_b32_e32 v8, 0
	s_cbranch_scc0 .LBB0_28
	s_mul_i32 s1, s0, 0x1800
	v_add_u32_e32 v8, s1, v2
	v_readlane_b32 s36, v247, 17
	v_ashrrev_i32_e32 v9, 31, v8
	v_readlane_b32 s40, v247, 21
	v_readlane_b32 s41, v247, 22
	v_readlane_b32 s37, v247, 18
	v_readlane_b32 s38, v247, 19
	v_lshl_add_u64 v[8:9], v[8:9], 2, s[40:41]
	global_load_dword v8, v[8:9], off
	v_readlane_b32 s39, v247, 20
	v_readlane_b32 s42, v247, 23
	v_readlane_b32 s43, v247, 24
	v_readlane_b32 s44, v247, 25
	v_readlane_b32 s45, v247, 26
	v_readlane_b32 s46, v247, 27
	v_readlane_b32 s47, v247, 28
	v_readlane_b32 s48, v247, 29
	v_readlane_b32 s49, v247, 30
	v_readlane_b32 s50, v247, 31
	v_readlane_b32 s51, v247, 32
	s_branch .LBB0_28

.LBB0_978:
	s_lshl_b32 s13, s39, 12
	s_or_b32 s12, s0, s9
	s_lshl_b32 s0, s13, 2
	v_cvt_pk_bf16_f32 v2, v2, s0
	ds_write_b16 v105, v2 offset:35840
	v_cvt_pk_bf16_f32 v2, v3, s0
	ds_write_b16 v105, v2 offset:35984
	v_cvt_pk_bf16_f32 v2, v4, s0
	ds_write_b16 v105, v2 offset:36128
	v_cvt_pk_bf16_f32 v2, v5, s0
	ds_write_b16 v105, v2 offset:36272
	v_cvt_pk_bf16_f32 v2, v6, s0
	s_waitcnt vmcnt(0)
	v_mul_f32_e32 v18, 0x3fb8aa3b, v20
	ds_write_b16 v105, v2 offset:36416
	v_cvt_pk_bf16_f32 v2, v7, s0
	v_exp_f32_e32 v107, v18
	ds_write_b16 v105, v2 offset:36560
	v_cvt_pk_bf16_f32 v2, v8, s0
	ds_write_b16 v105, v2 offset:36704
	v_cvt_pk_bf16_f32 v2, v9, s0
	ds_write_b16 v105, v2 offset:36848
	v_cvt_pk_bf16_f32 v2, v10, s0
	ds_write_b16 v105, v2 offset:36992
	v_cvt_pk_bf16_f32 v2, v11, s0
	v_mul_f32_e32 v18, 0xc3000000, v107
	ds_write_b16 v105, v2 offset:37136
	v_cvt_pk_bf16_f32 v2, v12, s0
	v_mul_f32_e32 v18, 0x3fb8aa3b, v18
	ds_write_b16 v105, v2 offset:37280
	v_cvt_pk_bf16_f32 v2, v13, s0
	v_exp_f32_e32 v18, v18
	ds_write_b16 v105, v2 offset:37424
	v_cvt_pk_bf16_f32 v2, v14, s0
	ds_write_b16 v105, v2 offset:37568
	v_cvt_pk_bf16_f32 v2, v15, s0
	s_and_b64 s[14:15], s[6:7], s[4:5]
	ds_write_b16 v105, v2 offset:37712
	v_cvt_pk_bf16_f32 v2, v16, s0
	s_or_b32 s6, s42, s35
	v_lshl_add_u64 v[20:21], v[84:85], 0, s[0:1]
	ds_write_b16 v105, v2 offset:37856
	v_cvt_pk_bf16_f32 v2, v17, s0
	s_and_b64 vcc, exec, s[14:15]
	v_lshlrev_b32_e32 v24, 2, v66
	ds_write_b16 v105, v2 offset:38000
	s_cbranch_vccz .LBB0_980
	s_ashr_i32 s13, s12, 31
	v_readlane_b32 s44, v247, 49
	s_lshl_b64 s[42:43], s[12:13], 18
	v_readlane_b32 s54, v247, 59
	v_lshl_add_u64 v[2:3], v[82:83], 0, s[42:43]
	v_readlane_b32 s55, v247, 60
	s_add_u32 s42, s54, s42
	s_addc_u32 s43, s55, s43
	v_lshl_add_u64 v[4:5], v[68:69], 2, s[42:43]
	v_mov_b32_e32 v25, v1
	v_lshl_add_u64 v[4:5], v[4:5], 0, v[24:25]
	v_add_co_u32_e32 v6, vcc, s60, v4
	s_ashr_i32 s7, s6, 31
	s_nop 0
	v_addc_co_u32_e32 v7, vcc, 0, v5, vcc
	s_nop 0
	s_nop 0
	s_lshl_b64 s[42:43], s[6:7], 16
	v_lshl_add_u64 v[6:7], v[20:21], 0, s[42:43]
	s_mov_b64 s[42:43], 0x4000
	v_lshl_add_u64 v[4:5], v[4:5], 0, s[42:43]
	v_readlane_b32 s45, v247, 50
	v_readlane_b32 s46, v247, 51
	v_readlane_b32 s47, v247, 52
	v_readlane_b32 s48, v247, 53
	v_readlane_b32 s49, v247, 54
	v_readlane_b32 s50, v247, 55
	v_readlane_b32 s51, v247, 56
	v_readlane_b32 s52, v247, 57
	v_readlane_b32 s53, v247, 58
	v_readlane_b32 s56, v247, 61
	v_readlane_b32 s57, v247, 62
	v_readlane_b32 s58, v247, 63
	v_readlane_b32 s59, v246, 0
	global_load_dwordx4 v[108:111], v[2:3], off
	global_load_dwordx4 v[112:115], v[2:3], off offset:16
	global_load_dwordx4 v[116:119], v[2:3], off offset:32
	global_load_dwordx4 v[120:123], v[2:3], off offset:48
	global_load_dwordx4 v[124:127], v[4:5], off
	global_load_dwordx4 v[128:131], v[4:5], off offset:16
	global_load_dwordx4 v[132:135], v[4:5], off offset:32
	global_load_dwordx4 v[136:139], v[4:5], off offset:48
	s_waitcnt vmcnt(0)
	v_fmac_f32_e32 v124, v26, v108
	v_fmac_f32_e32 v125, v26, v109
	v_fmac_f32_e32 v126, v26, v110
	v_fmac_f32_e32 v127, v26, v111
	v_fmac_f32_e32 v128, v26, v112
	v_fmac_f32_e32 v129, v26, v113
	v_fmac_f32_e32 v130, v26, v114
	v_fmac_f32_e32 v131, v26, v115
	v_fmac_f32_e32 v132, v26, v116
	v_fmac_f32_e32 v133, v26, v117
	v_fmac_f32_e32 v134, v26, v118
	v_fmac_f32_e32 v135, v26, v119
	v_fmac_f32_e32 v136, v26, v120
	v_fmac_f32_e32 v137, v26, v121
	v_fmac_f32_e32 v138, v26, v122
	v_fmac_f32_e32 v139, v26, v123
	global_store_dwordx4 v[6:7], v[124:127], off
	global_store_dwordx4 v[6:7], v[128:131], off offset:16
	global_store_dwordx4 v[6:7], v[132:135], off offset:32
	global_store_dwordx4 v[6:7], v[136:139], off offset:48

.LBB0_985:
	s_waitcnt vmcnt(3)
	v_cvt_pk_bf16_f32 v2, v2, s0
	ds_write_b16 v105, v2 offset:45056
	v_cvt_pk_bf16_f32 v2, v3, s0
	ds_write_b16 v105, v2 offset:45200
	v_cvt_pk_bf16_f32 v2, v4, s0
	ds_write_b16 v105, v2 offset:45344
	v_cvt_pk_bf16_f32 v2, v5, s0
	ds_write_b16 v105, v2 offset:45488
	s_waitcnt vmcnt(2)
	v_cvt_pk_bf16_f32 v2, v6, s0
	ds_write_b16 v105, v2 offset:45632
	v_cvt_pk_bf16_f32 v2, v7, s0
	ds_write_b16 v105, v2 offset:45776
	v_cvt_pk_bf16_f32 v2, v8, s0
	ds_write_b16 v105, v2 offset:45920
	v_cvt_pk_bf16_f32 v2, v9, s0
	ds_write_b16 v105, v2 offset:46064
	s_waitcnt vmcnt(1)
	v_cvt_pk_bf16_f32 v2, v10, s0
	ds_write_b16 v105, v2 offset:46208
	v_cvt_pk_bf16_f32 v2, v11, s0
	ds_write_b16 v105, v2 offset:46352
	v_cvt_pk_bf16_f32 v2, v12, s0
	ds_write_b16 v105, v2 offset:46496
	v_cvt_pk_bf16_f32 v2, v13, s0
	ds_write_b16 v105, v2 offset:46640
	s_waitcnt vmcnt(0)
	v_cvt_pk_bf16_f32 v2, v14, s0
	ds_write_b16 v105, v2 offset:46784
	v_cvt_pk_bf16_f32 v2, v15, s0
	ds_write_b16 v105, v2 offset:46928
	v_cvt_pk_bf16_f32 v2, v16, s0
	ds_write_b16 v105, v2 offset:47072
	v_cvt_pk_bf16_f32 v2, v17, s0
	s_andn2_b64 vcc, exec, s[14:15]
	ds_write_b16 v105, v2 offset:47216
	s_cbranch_vccnz .LBB0_987
	s_or_b32 s8, s12, 1
	s_ashr_i32 s9, s8, 31
	v_readlane_b32 s44, v247, 49
	s_lshl_b64 s[8:9], s[8:9], 18
	v_readlane_b32 s54, v247, 59
	v_lshl_add_u64 v[2:3], v[82:83], 0, s[8:9]
	v_readlane_b32 s55, v247, 60
	s_add_u32 s8, s54, s8
	s_addc_u32 s9, s55, s9
	v_lshl_add_u64 v[4:5], v[68:69], 2, s[8:9]
	v_mov_b32_e32 v25, v1
	v_lshl_add_u64 v[4:5], v[4:5], 0, v[24:25]
	v_add_co_u32_e32 v6, vcc, s0, v4
	s_or_b32 s6, s6, 1
	s_nop 0
	v_addc_co_u32_e32 v7, vcc, 0, v5, vcc
	s_nop 0
	s_nop 0
	s_ashr_i32 s7, s6, 31
	s_lshl_b64 s[6:7], s[6:7], 16
	s_mov_b64 s[8:9], 0x4000
	v_lshl_add_u64 v[6:7], v[20:21], 0, s[6:7]
	v_lshl_add_u64 v[4:5], v[4:5], 0, s[8:9]
	v_readlane_b32 s45, v247, 50
	v_readlane_b32 s46, v247, 51
	v_readlane_b32 s47, v247, 52
	v_readlane_b32 s48, v247, 53
	v_readlane_b32 s49, v247, 54
	v_readlane_b32 s50, v247, 55
	v_readlane_b32 s51, v247, 56
	v_readlane_b32 s52, v247, 57
	v_readlane_b32 s53, v247, 58
	v_readlane_b32 s56, v247, 61
	v_readlane_b32 s57, v247, 62
	v_readlane_b32 s58, v247, 63
	v_readlane_b32 s59, v246, 0
	global_load_dwordx4 v[108:111], v[4:5], off
	global_load_dwordx4 v[112:115], v[4:5], off offset:16
	global_load_dwordx4 v[116:119], v[4:5], off offset:32
	global_load_dwordx4 v[120:123], v[4:5], off offset:48
	global_load_dwordx4 v[124:127], v[2:3], off
	global_load_dwordx4 v[128:131], v[2:3], off offset:16
	global_load_dwordx4 v[132:135], v[2:3], off offset:32
	global_load_dwordx4 v[136:139], v[2:3], off offset:48
	s_waitcnt vmcnt(0)
	v_fmac_f32_e32 v124, v18, v108
	v_fmac_f32_e32 v125, v18, v109
	v_fmac_f32_e32 v126, v18, v110
	v_fmac_f32_e32 v127, v18, v111
	v_fmac_f32_e32 v128, v18, v112
	v_fmac_f32_e32 v129, v18, v113
	v_fmac_f32_e32 v130, v18, v114
	v_fmac_f32_e32 v131, v18, v115
	v_fmac_f32_e32 v132, v18, v116
	v_fmac_f32_e32 v133, v18, v117
	v_fmac_f32_e32 v134, v18, v118
	v_fmac_f32_e32 v135, v18, v119
	v_fmac_f32_e32 v136, v18, v120
	v_fmac_f32_e32 v137, v18, v121
	v_fmac_f32_e32 v138, v18, v122
	v_fmac_f32_e32 v139, v18, v123
	global_store_dwordx4 v[6:7], v[124:127], off
	global_store_dwordx4 v[6:7], v[128:131], off offset:16
	global_store_dwordx4 v[6:7], v[132:135], off offset:32
	global_store_dwordx4 v[6:7], v[136:139], off offset:48
